# one static s_setprio 1 at kernel entry for workgroups 256..511 (the later-dispatched workgroup of each CU)
# speedup vs baseline: 1.5972x; 1.0052x over previous
_Z14fwd_megakernel6Params:
	s_load_dwordx16 s[76:91], s[0:1], 0x0
	s_load_dwordx4 s[52:55], s[0:1], 0xa0
	s_load_dwordx8 s[24:31], s[0:1], 0x80
	s_load_dword s59, s[0:1], 0xb0
	v_writelane_b32 v251, s2, 0
	s_cmp_ge_u32 s2, 0x100
	s_cbranch_scc0 .Lprio_done
	s_setprio 1
.Lprio_done:
	s_add_u32 s2, s0, 0xb0
	s_addc_u32 s3, s1, 0
	v_writelane_b32 v251, s2, 1
	s_waitcnt lgkmcnt(0)
	s_cmp_lg_u32 s54, 0
	v_writelane_b32 v251, s3, 2
	s_cselect_b64 s[2:3], -1, 0
	v_writelane_b32 v251, s2, 3
	s_cmp_eq_u32 s54, 0
	s_nop 0
	v_writelane_b32 v251, s3, 4
	s_branch .LBB0_12
	v_and_b32_e32 v1, 0x3fffffff, v0
	v_cmp_eq_u32_e32 vcc, 0, v1
	s_barrier
	s_and_saveexec_b64 s[2:3], vcc
	s_cbranch_execz .LBB0_11
	v_readlane_b32 s4, v251, 1
	v_readlane_b32 s5, v251, 2
	buffer_wbl2 sc1
	s_load_dwordx2 s[4:5], s[4:5], 0x58
	s_mov_b64 s[6:7], exec
	v_mbcnt_lo_u32_b32 v1, s6, 0
	v_mbcnt_hi_u32_b32 v1, s7, v1
	v_cmp_eq_u32_e32 vcc, 0, v1
	s_waitcnt lgkmcnt(0)
	s_load_dword s10, s[4:5], 0x28
	s_and_saveexec_b64 s[8:9], vcc
	s_cbranch_execz .LBB0_4
	s_bcnt1_i32_b64 s6, s[6:7]
	v_mov_b32_e32 v2, 0
	v_mov_b32_e32 v3, s6
	global_atomic_add v2, v2, v3, s[4:5] offset:32 sc0
